# attention main loop: optimistic online softmax - exps first, per-lane sum>2^13 check trips the original max+rescale path (exact same math, reference still moves when tile max exceeds it by >8)
# speedup vs baseline: 1.0232x; 1.0232x over previous
.LBB0_554:
	s_or_b64 exec, exec, s[6:7]
	global_load_dwordx4 v[2:5], v[174:175], off
	s_add_i32 s7, s64, 3
	s_and_b32 s6, s7, 1
	s_cmp_gt_i32 s7, s26
	s_cbranch_scc1 .LBB0_558
	s_mul_i32 s7, s6, 0x3400
	v_add_u32_e32 v0, s7, v169
	ds_read_b128 v[6:9], v0
	ds_read_b128 v[10:13], v0 offset:32
	ds_read_b128 v[128:131], v0 offset:6656
	ds_read_b128 v[132:135], v0 offset:6688
	ds_read_b128 v[136:139], v0 offset:64
	ds_read_b128 v[140:143], v0 offset:96
	ds_read_b128 v[144:147], v0 offset:6720
	ds_read_b128 v[148:151], v0 offset:6752
	ds_read_b128 v[180:183], v0 offset:128
	ds_read_b128 v[184:187], v0 offset:160
	ds_read_b128 v[188:191], v0 offset:6784
	ds_read_b128 v[192:195], v0 offset:6816
	s_waitcnt lgkmcnt(8)
	v_mfma_f32_32x32x16_bf16 v[80:95], v[6:9], v[116:119], v[48:63]
	v_mfma_f32_32x32x16_bf16 v[64:79], v[128:131], v[116:119], v[48:63]
	v_mfma_f32_32x32x16_bf16 v[80:95], v[10:13], v[112:115], v[80:95]
	v_mfma_f32_32x32x16_bf16 v[64:79], v[132:135], v[112:115], v[64:79]
	s_waitcnt lgkmcnt(4)
	v_mfma_f32_32x32x16_bf16 v[80:95], v[136:139], v[108:111], v[80:95]
	v_mfma_f32_32x32x16_bf16 v[64:79], v[144:147], v[108:111], v[64:79]
	v_mfma_f32_32x32x16_bf16 v[80:95], v[140:143], v[104:107], v[80:95]
	v_mfma_f32_32x32x16_bf16 v[64:79], v[148:151], v[104:107], v[64:79]
	s_waitcnt lgkmcnt(0)
	v_mfma_f32_32x32x16_bf16 v[80:95], v[180:183], v[120:123], v[80:95]
	v_mfma_f32_32x32x16_bf16 v[64:79], v[188:191], v[120:123], v[64:79]
	v_mfma_f32_32x32x16_bf16 v[80:95], v[184:187], v[124:127], v[80:95]
	v_mfma_f32_32x32x16_bf16 v[64:79], v[192:195], v[124:127], v[64:79]
	s_mul_i32 s7, s6, 0x2200
	v_add_u32_e32 v0, s7, v165
	v_add_u32_e32 v6, 0x6800, v0
	v_add_u32_e32 v0, 0x7800, v0
	ds_read2_b64 v[148:151], v6 offset1:2
	ds_read2_b64 v[144:147], v6 offset0:4 offset1:6
	ds_read2_b64 v[140:143], v6 offset0:8 offset1:10
	ds_read2_b64 v[136:139], v6 offset0:12 offset1:14
	ds_read2_b64 v[132:135], v0 offset0:32 offset1:34
	ds_read2_b64 v[128:131], v0 offset0:36 offset1:38
	ds_read2_b64 v[10:13], v0 offset0:40 offset1:42
	ds_read2_b64 v[6:9], v0 offset0:44 offset1:46
.LBB0_557:
	v_exp_f32_e32 v196, v80
	v_exp_f32_e32 v212, v64
	v_exp_f32_e32 v197, v81
	v_exp_f32_e32 v213, v65
	v_exp_f32_e32 v198, v82
	v_exp_f32_e32 v214, v66
	v_add_f32_e32 v229, v212, v196
	v_exp_f32_e32 v199, v83
	v_exp_f32_e32 v215, v67
	v_add_f32_e32 v230, v213, v197
	v_add_f32_e32 v229, v230, v229
	v_exp_f32_e32 v200, v84
	v_exp_f32_e32 v216, v68
	v_add_f32_e32 v228, v214, v198
	v_add_f32_e32 v229, v228, v229
	v_exp_f32_e32 v201, v85
	v_exp_f32_e32 v217, v69
	v_add_f32_e32 v230, v215, v199
	v_add_f32_e32 v229, v230, v229
	v_exp_f32_e32 v202, v86
	v_exp_f32_e32 v218, v70
	v_add_f32_e32 v228, v216, v200
	v_add_f32_e32 v229, v228, v229
	v_exp_f32_e32 v203, v87
	v_exp_f32_e32 v219, v71
	v_add_f32_e32 v230, v217, v201
	v_add_f32_e32 v229, v230, v229
	v_exp_f32_e32 v204, v88
	v_exp_f32_e32 v220, v72
	v_add_f32_e32 v228, v218, v202
	v_add_f32_e32 v229, v228, v229
	v_exp_f32_e32 v205, v89
	v_exp_f32_e32 v221, v73
	v_add_f32_e32 v230, v219, v203
	v_add_f32_e32 v229, v230, v229
	v_exp_f32_e32 v206, v90
	v_exp_f32_e32 v222, v74
	v_add_f32_e32 v228, v220, v204
	v_add_f32_e32 v229, v228, v229
	v_exp_f32_e32 v207, v91
	v_exp_f32_e32 v223, v75
	v_add_f32_e32 v230, v221, v205
	v_add_f32_e32 v229, v230, v229
	v_exp_f32_e32 v208, v92
	v_exp_f32_e32 v224, v76
	v_add_f32_e32 v228, v222, v206
	v_add_f32_e32 v229, v228, v229
	v_exp_f32_e32 v209, v93
	v_exp_f32_e32 v225, v77
	v_add_f32_e32 v230, v223, v207
	v_add_f32_e32 v229, v230, v229
	v_exp_f32_e32 v210, v94
	v_exp_f32_e32 v226, v78
	v_add_f32_e32 v228, v224, v208
	v_add_f32_e32 v229, v228, v229
	v_exp_f32_e32 v211, v95
	v_exp_f32_e32 v227, v79
	v_add_f32_e32 v230, v225, v209
	v_add_f32_e32 v229, v230, v229
	v_add_f32_e32 v228, v226, v210
	v_add_f32_e32 v229, v228, v229
	v_add_f32_e32 v230, v227, v211
	v_add_f32_e32 v231, v230, v229
	v_cmp_lt_f32_e32 vcc, 0x46000000, v231
	s_cbranch_vccnz .Lat_slow
	v_cvt_pk_bf16_f32 v64, v196, v197
	v_cvt_pk_bf16_f32 v65, v198, v199
	v_cvt_pk_bf16_f32 v66, v200, v201
	v_cvt_pk_bf16_f32 v67, v202, v203
	v_cvt_pk_bf16_f32 v68, v204, v205
	v_cvt_pk_bf16_f32 v69, v206, v207
	v_cvt_pk_bf16_f32 v70, v208, v209
	v_cvt_pk_bf16_f32 v71, v210, v211
	v_cvt_pk_bf16_f32 v72, v212, v213
	v_cvt_pk_bf16_f32 v73, v214, v215
	v_cvt_pk_bf16_f32 v74, v216, v217
	v_cvt_pk_bf16_f32 v75, v218, v219
	v_cvt_pk_bf16_f32 v76, v220, v221
	v_cvt_pk_bf16_f32 v77, v222, v223
	v_cvt_pk_bf16_f32 v78, v224, v225
	v_cvt_pk_bf16_f32 v79, v226, v227
	v_add_f32_e32 v159, v159, v231
	s_waitcnt lgkmcnt(0)
	v_mfma_f32_32x32x16_bf16 v[32:47], v[148:151], v[64:67], v[32:47]
	v_mfma_f32_32x32x16_bf16 v[16:31], v[132:135], v[64:67], v[16:31]
	v_mfma_f32_32x32x16_bf16 v[32:47], v[144:147], v[68:71], v[32:47]
	v_mfma_f32_32x32x16_bf16 v[16:31], v[128:131], v[68:71], v[16:31]
	v_mfma_f32_32x32x16_bf16 v[32:47], v[140:143], v[72:75], v[32:47]
	v_mfma_f32_32x32x16_bf16 v[16:31], v[10:13], v[72:75], v[16:31]
	v_mfma_f32_32x32x16_bf16 v[32:47], v[136:139], v[76:79], v[32:47]
	v_mfma_f32_32x32x16_bf16 v[16:31], v[6:9], v[76:79], v[16:31]

.Lat_slow:
	v_max_f32_e32 v15, v65, v65
	v_max_f32_e32 v161, v64, v64
	v_max_f32_e32 v15, v161, v15
	v_max3_f32 v0, v80, v81, v82
	v_max3_f32 v15, v15, v66, v67
	v_max3_f32 v0, v0, v83, v84
	v_max3_f32 v15, v15, v68, v69
	v_max3_f32 v0, v0, v85, v86
	v_max3_f32 v15, v15, v70, v71
	v_max3_f32 v0, v0, v87, v88
	v_max3_f32 v15, v15, v72, v73
	v_max3_f32 v0, v0, v89, v90
	v_max3_f32 v15, v15, v74, v75
	v_max3_f32 v0, v0, v91, v92
	v_max3_f32 v15, v15, v76, v77
	v_max3_f32 v0, v0, v93, v94
	v_max3_f32 v15, v15, v78, v79
	v_max3_f32 v0, v0, v95, v15
	v_mov_b32_e32 v15, v0
	s_nop 1
	v_permlane32_swap_b32_e32 v0, v15
	v_max_f32_e32 v15, v15, v15
	v_max_f32_e32 v0, v0, v0
	v_max_f32_e32 v0, v0, v15
	v_cmp_lt_f32_e32 vcc, s56, v0
	s_nop 0
	v_cndmask_b32_e32 v0, 0, v0, vcc
	v_exp_f32_e64 v180, -v0
	v_add_f32_e32 v158, v158, v0
	v_xor_b32_e32 v48, 0x80000000, v158
	v_mov_b32_e32 v49, v48
	v_mov_b32_e32 v50, v48
	v_mov_b32_e32 v51, v48
	v_mov_b32_e32 v52, v48
	v_mov_b32_e32 v53, v48
	v_mov_b32_e32 v54, v48
	v_mov_b32_e32 v55, v48
	v_mov_b32_e32 v56, v48
	v_mov_b32_e32 v57, v48
	v_mov_b32_e32 v58, v48
	v_mov_b32_e32 v59, v48
	v_mov_b32_e32 v60, v48
	v_mov_b32_e32 v61, v48
	v_mov_b32_e32 v62, v48
	v_mov_b32_e32 v63, v48
	v_pk_add_f32 v[80:81], v[80:81], v[0:1] op_sel_hi:[1,0] neg_lo:[0,1] neg_hi:[0,1]
	v_pk_add_f32 v[64:65], v[64:65], v[0:1] op_sel_hi:[1,0] neg_lo:[0,1] neg_hi:[0,1]
	v_pk_add_f32 v[82:83], v[82:83], v[0:1] op_sel_hi:[1,0] neg_lo:[0,1] neg_hi:[0,1]
	v_pk_add_f32 v[66:67], v[66:67], v[0:1] op_sel_hi:[1,0] neg_lo:[0,1] neg_hi:[0,1]
	v_pk_add_f32 v[84:85], v[84:85], v[0:1] op_sel_hi:[1,0] neg_lo:[0,1] neg_hi:[0,1]
	v_pk_add_f32 v[68:69], v[68:69], v[0:1] op_sel_hi:[1,0] neg_lo:[0,1] neg_hi:[0,1]
	v_pk_add_f32 v[86:87], v[86:87], v[0:1] op_sel_hi:[1,0] neg_lo:[0,1] neg_hi:[0,1]
	v_pk_add_f32 v[70:71], v[70:71], v[0:1] op_sel_hi:[1,0] neg_lo:[0,1] neg_hi:[0,1]
	v_pk_add_f32 v[88:89], v[88:89], v[0:1] op_sel_hi:[1,0] neg_lo:[0,1] neg_hi:[0,1]
	v_pk_add_f32 v[72:73], v[72:73], v[0:1] op_sel_hi:[1,0] neg_lo:[0,1] neg_hi:[0,1]
	v_pk_add_f32 v[90:91], v[90:91], v[0:1] op_sel_hi:[1,0] neg_lo:[0,1] neg_hi:[0,1]
	v_pk_add_f32 v[74:75], v[74:75], v[0:1] op_sel_hi:[1,0] neg_lo:[0,1] neg_hi:[0,1]
	v_pk_add_f32 v[92:93], v[92:93], v[0:1] op_sel_hi:[1,0] neg_lo:[0,1] neg_hi:[0,1]
	v_pk_add_f32 v[76:77], v[76:77], v[0:1] op_sel_hi:[1,0] neg_lo:[0,1] neg_hi:[0,1]
	v_pk_add_f32 v[94:95], v[94:95], v[0:1] op_sel_hi:[1,0] neg_lo:[0,1] neg_hi:[0,1]
	v_pk_add_f32 v[78:79], v[78:79], v[0:1] op_sel_hi:[1,0] neg_lo:[0,1] neg_hi:[0,1]
	v_pk_mul_f32 v[46:47], v[46:47], v[180:181] op_sel_hi:[1,0]
	v_pk_mul_f32 v[44:45], v[44:45], v[180:181] op_sel_hi:[1,0]
	v_pk_mul_f32 v[42:43], v[42:43], v[180:181] op_sel_hi:[1,0]
	v_pk_mul_f32 v[40:41], v[40:41], v[180:181] op_sel_hi:[1,0]
	v_pk_mul_f32 v[38:39], v[38:39], v[180:181] op_sel_hi:[1,0]
	v_pk_mul_f32 v[36:37], v[36:37], v[180:181] op_sel_hi:[1,0]
	v_pk_mul_f32 v[34:35], v[34:35], v[180:181] op_sel_hi:[1,0]
	v_pk_mul_f32 v[32:33], v[32:33], v[180:181] op_sel_hi:[1,0]
	v_pk_mul_f32 v[30:31], v[30:31], v[180:181] op_sel_hi:[1,0]
	v_pk_mul_f32 v[28:29], v[28:29], v[180:181] op_sel_hi:[1,0]
	v_pk_mul_f32 v[26:27], v[26:27], v[180:181] op_sel_hi:[1,0]
	v_pk_mul_f32 v[24:25], v[24:25], v[180:181] op_sel_hi:[1,0]
	v_pk_mul_f32 v[22:23], v[22:23], v[180:181] op_sel_hi:[1,0]
	v_pk_mul_f32 v[20:21], v[20:21], v[180:181] op_sel_hi:[1,0]
	v_pk_mul_f32 v[18:19], v[18:19], v[180:181] op_sel_hi:[1,0]
	v_pk_mul_f32 v[16:17], v[16:17], v[180:181] op_sel_hi:[1,0]
	v_mul_f32_e32 v159, v159, v180
	s_branch .LBB0_557
